# MLA loop trim: saddr global loads, artefact s_nop removal, folded adds, permlane pads filled, relaxed lgkmcnt
# speedup vs baseline: 1.0080x; 1.0080x over previous
.LBB0_708:
	s_mov_b64 s[4:5], -1
	s_and_b64 vcc, exec, s[22:23]
	s_cbranch_vccz .LBB0_692
	s_ashr_i32 s4, s34, 31
	s_lshr_b32 s4, s4, 24
	s_add_i32 s5, s34, s4
	s_ashr_i32 s4, s5, 8
	s_and_b32 s5, s5, 0xffffff00
	s_sub_i32 s23, s34, s5
	s_bfe_u32 s5, s23, 0x20001
	s_ashr_i32 s26, s23, 3
	s_lshl_b32 s23, s23, 5
	s_and_b32 s23, s23, 32
	s_lshl_b32 s22, s4, 2
	s_add_i32 s26, s23, s26
	s_or_b32 s22, s5, s22
	s_ashr_i32 s27, s26, 31
	s_mul_i32 s30, s26, 0xc0000
	s_mul_hi_i32 s23, s26, 0xc0000
	s_add_u32 s34, s3, s30
	s_mul_i32 s30, s22, 0xc0
	s_addc_u32 s23, s12, s23
	s_ashr_i32 s31, s30, 31
	s_lshl_b64 s[30:31], s[30:31], 1
	s_add_u32 s52, s34, s30
	v_mov_b32_e32 v4, v0
	s_addc_u32 s53, s23, s31
	s_movk_i32 s56, 0xffe0
	v_ashrrev_i32_e32 v2, 1, v4
	v_bfe_u32 v221, v4, 5, 1
	v_bfi_b32 v212, s56, v2, v4
	v_mov_b64_e32 v[2:3], s[52:53]
	s_movk_i32 s52, 0xc00
	v_mad_i64_i32 v[2:3], s[52:53], v212, s52, v[2:3]
	v_lshlrev_b32_e32 v186, 5, v221
	s_lshl_b32 s30, s22, 7
	v_and_b32_e32 v18, 31, v4
	v_lshl_add_u64 v[10:11], v[2:3], 0, v[186:187]
	v_lshlrev_b32_e32 v2, 3, v4
	s_ashr_i32 s31, s30, 31
	v_and_b32_e32 v90, 56, v2
	v_mul_u32_u24_e32 v2, 0x90, v18
	s_add_u32 s54, s13, s30
	v_add3_u32 v223, 0, v2, v186
	v_mov_b32_e32 v2, s85
	s_addc_u32 s55, s24, s31
	s_ashr_i32 s23, s22, 31
	v_ashrrev_i32_e32 v12, 3, v4
	v_mad_u32_u24 v2, v18, s86, v2
	s_lshl_b64 s[34:35], s[22:23], 21
	v_add_u32_e32 v222, v2, v186
	v_lshlrev_b32_e32 v2, 4, v4
	v_ashrrev_i32_e32 v13, 31, v12
	s_add_u32 s36, s25, s34
	v_ashrrev_i32_e32 v19, 2, v4
	v_and_b32_e32 v20, 48, v2
	v_lshlrev_b64 v[66:67], 10, v[12:13]
	s_addc_u32 s37, s28, s35
	v_lshl_or_b32 v186, v19, 14, v20
	v_lshl_add_u64 v[2:3], s[54:55], 0, v[66:67]
	v_lshlrev_b32_e32 v68, 1, v90
	v_mov_b32_e32 v69, v187
	v_lshl_or_b32 v214, v12, 6, v90
	v_lshl_add_u64 v[14:15], v[2:3], 0, v[68:69]
	global_load_dwordx4 v[2:5], v186, s[36:37]
	global_load_dwordx4 v[6:9], v[14:15], off
	global_load_dwordx2 v[16:17], v214, s[10:11]
	global_load_dwordx4 v[196:199], v[10:11], off offset:336
	s_movk_i32 s52, 0x90
	v_mul_lo_u32 v13, v19, s86
	v_mul_lo_u32 v69, v12, s52
	v_mul_lo_u32 v91, v12, s86
	s_mov_b32 s52, 0x10000
	v_add3_u32 v224, 0, v13, v20
	v_add_u32_e32 v12, 0, v69
	v_add_u32_e32 v13, s85, v91
	global_load_dwordx4 v[150:153], v[10:11], off offset:272
	global_load_dwordx4 v[146:149], v[10:11], off offset:256
	global_load_dwordx4 v[174:177], v[10:11], off offset:320
	global_load_dwordx4 v[200:203], v[10:11], off offset:144
	global_load_dwordx4 v[180:183], v[10:11], off offset:128
	global_load_dwordx4 v[192:195], v[10:11], off offset:16
	global_load_dwordx4 v[168:171], v[10:11], off
	global_load_dwordx4 v[188:191], v[10:11], off offset:80
	global_load_dwordx4 v[162:165], v[10:11], off offset:64
	v_add_co_u32_e32 v10, vcc, s52, v14
	v_add_u32_e32 v225, v12, v68
	v_add_u32_e32 v226, v13, v90
	v_addc_co_u32_e32 v11, vcc, 0, v15, vcc
	s_waitcnt vmcnt(0)
	s_mov_b32 s52, 0
	s_mov_b32 s53, s52
	s_mov_b32 s54, s52
	s_mov_b32 s55, s52
	s_mov_b32 s56, s52
	s_mov_b32 s57, s52
	s_mov_b32 s58, s52
	s_mov_b32 s59, s52
	s_mov_b32 s60, s52
	s_mov_b32 s61, s52
	s_mov_b32 s62, s52
	s_mov_b32 s63, s52
	s_mov_b32 s64, s52
	s_mov_b32 s65, s52
	s_mov_b32 s66, s52
	s_mov_b32 s67, s52
	v_ashrrev_i32_e32 v213, 31, v212
	s_waitcnt vmcnt(0)
	v_add_u32_e32 v199, 0xc000, v223
	v_mov_b32_e32 v215, v187
	ds_write_b128 v224, v[2:5]
	ds_write_b128 v225, v[6:9] offset:49152
	ds_write_b64 v226, v[16:17]
	s_waitcnt lgkmcnt(0)
	s_barrier
	global_load_dwordx4 v[76:79], v186, s[36:37] offset:64
	global_load_dwordx4 v[80:83], v[10:11], off
	global_load_dwordx2 v[88:89], v214, s[14:15]
	v_lshlrev_b32_e32 v2, 6, v18
	ds_read_b128 v[18:21], v223 offset:49152
	ds_read_b128 v[28:31], v223 offset:49168
	ds_read_b128 v[24:27], v223 offset:53760
	ds_read_b128 v[50:53], v223 offset:53776
	ds_read_b128 v[62:65], v223 offset:49232
	ds_read_b128 v[58:61], v223 offset:49216
	s_waitcnt lgkmcnt(4)
	v_mov_b32_e32 v22, v28
	v_mov_b32_e32 v23, v29
	v_mov_b32_e32 v178, v196
	v_mov_b32_e32 v179, v197
	v_sub_u32_e32 v191, v223, v2
	v_mov_b64_e32 v[2:3], s[52:53]
	v_mfma_scale_f32_32x32x64_f8f6f4 v[34:49], v[18:23], v[174:179], 0, v30, v198 op_sel_hi:[0,0,0] cbsz:2 blgp:2
	v_mov_b64_e32 v[4:5], s[54:55]
	v_mov_b64_e32 v[6:7], s[56:57]
	v_mov_b64_e32 v[8:9], s[58:59]
	v_mov_b64_e32 v[10:11], s[60:61]
	v_mov_b64_e32 v[12:13], s[62:63]
	v_mov_b64_e32 v[14:15], s[64:65]
	v_mov_b64_e32 v[16:17], s[66:67]
	s_waitcnt lgkmcnt(2)
	v_mov_b32_e32 v28, v50
	v_mov_b32_e32 v29, v51
	ds_read_b128 v[70:73], v223 offset:53824
	ds_read_b128 v[84:87], v223 offset:53840
	v_mfma_scale_f32_32x32x64_f8f6f4 v[18:33], v[24:29], v[174:179], 0, v52, v198 op_sel_hi:[0,0,0] cbsz:2 blgp:2
	v_mov_b32_e32 v184, v200
	v_mov_b32_e32 v185, v201
	ds_read_b128 v[50:53], v222
	ds_read_b128 v[54:57], v222 offset:16
	s_waitcnt lgkmcnt(4)
	v_mfma_scale_f32_32x32x64_f8f6f4 v[34:49], v[58:63], v[180:185], v[34:49], v64, v202 op_sel_hi:[0,0,0] cbsz:2 blgp:2
	s_waitcnt lgkmcnt(2)
	v_mov_b32_e32 v74, v84
	v_mov_b32_e32 v75, v85
	ds_read_b128 v[58:61], v222 offset:2560
	ds_read_b128 v[62:65], v222 offset:2576
	v_mfma_scale_f32_32x32x64_f8f6f4 v[18:33], v[70:75], v[180:185], v[18:33], v86, v202 op_sel_hi:[0,0,0] cbsz:2 blgp:2
	s_waitcnt lgkmcnt(2)
	v_mfma_scale_f32_32x32x64_f8f6f4 v[34:49], v[50:57], v[146:153], v[34:49], v220, v1 op_sel_hi:[0,0,0]
	s_waitcnt lgkmcnt(0)
	v_mfma_scale_f32_32x32x64_f8f6f4 v[18:33], v[58:65], v[146:153], v[18:33], v220, v1 op_sel_hi:[0,0,0]
	v_add_u32_e32 v50, s38, v69
	v_add_u32_e32 v203, v50, v68
	v_add_u32_e32 v50, s87, v91
	v_add_u32_e32 v227, v50, v90
	s_nop 13
	v_max3_f32 v50, v34, s88, v35
	s_waitcnt vmcnt(0)
	v_max3_f32 v50, v50, v36, v37
	v_max3_f32 v50, v50, v38, v39
	v_max3_f32 v50, v50, v40, v41
	s_waitcnt vmcnt(2)
	ds_write_b128 v224, v[76:79] offset:16384
	s_waitcnt vmcnt(1)
	ds_write_b128 v203, v[80:83]
	s_waitcnt vmcnt(0)
	ds_write_b64 v227, v[88:89]
	s_nop 0
	v_max3_f32 v50, v50, v42, v43
	v_max3_f32 v50, v50, v44, v45
	v_max3_f32 v50, v50, v46, v47
	v_max3_f32 v50, v50, v48, v49
	s_nop 0
	v_max3_f32 v50, v50, v18, v19
	v_max3_f32 v50, v50, v20, v21
	v_max3_f32 v50, v50, v22, v23
	v_max3_f32 v50, v50, v24, v25
	s_nop 0
	v_max3_f32 v50, v50, v26, v27
	v_max3_f32 v50, v50, v28, v29
	v_max3_f32 v50, v50, v30, v31
	v_max3_f32 v50, v50, v32, v33
	s_nop 0
	v_mov_b32_e32 v51, v50
	s_nop 1
	v_permlane32_swap_b32_e32 v50, v51
	v_max_f32_e32 v51, v51, v51
	v_max_f32_e32 v50, v50, v50
	v_max_f32_e32 v50, v50, v51
	v_add_f32_e32 v50, -4.0, v50
	v_sub_f32_e32 v97, v49, v50
	v_sub_f32_e32 v96, v48, v50
	v_sub_f32_e32 v95, v47, v50
	v_sub_f32_e32 v94, v46, v50
	v_sub_f32_e32 v93, v45, v50
	v_sub_f32_e32 v92, v44, v50
	v_sub_f32_e32 v91, v43, v50
	v_sub_f32_e32 v90, v42, v50
	v_sub_f32_e32 v89, v41, v50
	v_sub_f32_e32 v88, v40, v50
	v_sub_f32_e32 v87, v39, v50
	v_sub_f32_e32 v86, v38, v50
	v_sub_f32_e32 v85, v37, v50
	v_sub_f32_e32 v84, v36, v50
	v_sub_f32_e32 v35, v35, v50
	v_sub_f32_e32 v34, v34, v50
	v_sub_f32_e32 v113, v33, v50
	v_sub_f32_e32 v112, v32, v50
	v_sub_f32_e32 v111, v31, v50
	v_sub_f32_e32 v110, v30, v50
	v_sub_f32_e32 v109, v29, v50
	v_sub_f32_e32 v108, v28, v50
	v_sub_f32_e32 v107, v27, v50
	v_sub_f32_e32 v106, v26, v50
	v_sub_f32_e32 v105, v25, v50
	v_sub_f32_e32 v104, v24, v50
	v_sub_f32_e32 v103, v23, v50
	v_sub_f32_e32 v102, v22, v50
	v_sub_f32_e32 v101, v21, v50
	v_sub_f32_e32 v100, v20, v50
	v_sub_f32_e32 v99, v19, v50
	v_sub_f32_e32 v18, v18, v50
	v_sub_f32_e32 v50, 0, v50
	v_mov_b32_e32 v51, v50
	v_mov_b32_e32 v52, v50
	v_mov_b32_e32 v53, v50
	v_mov_b32_e32 v54, v50
	v_mov_b32_e32 v55, v50
	v_mov_b32_e32 v56, v50
	v_mov_b32_e32 v57, v50
	v_mov_b32_e32 v58, v50
	v_mov_b32_e32 v59, v50
	v_mov_b32_e32 v60, v50
	v_mov_b32_e32 v61, v50
	v_mov_b32_e32 v62, v50
	v_mov_b32_e32 v63, v50
	v_mov_b32_e32 v64, v50
	v_mov_b32_e32 v65, v50
	v_mov_b32_e32 v228, 1.0
	v_exp_f32_e32 v82, v34
	v_exp_f32_e32 v83, v35
	s_nop 0
	v_exp_f32_e32 v84, v84
	v_exp_f32_e32 v85, v85
	v_exp_f32_e32 v86, v86
	s_nop 0
	v_exp_f32_e32 v87, v87
	v_exp_f32_e32 v88, v88
	v_exp_f32_e32 v89, v89
	s_nop 0
	v_exp_f32_e32 v90, v90
	v_exp_f32_e32 v91, v91
	v_exp_f32_e32 v92, v92
	s_nop 0
	v_exp_f32_e32 v93, v93
	v_exp_f32_e32 v94, v94
	v_exp_f32_e32 v95, v95
	s_nop 0
	v_exp_f32_e32 v96, v96
	v_exp_f32_e32 v97, v97
	v_exp_f32_e32 v98, v18
	s_nop 0
	v_exp_f32_e32 v99, v99
	v_exp_f32_e32 v100, v100
	v_exp_f32_e32 v101, v101
	s_nop 0
	v_exp_f32_e32 v102, v102
	v_exp_f32_e32 v103, v103
	v_exp_f32_e32 v104, v104
	s_nop 0
	v_exp_f32_e32 v105, v105
	v_exp_f32_e32 v106, v106
	v_exp_f32_e32 v107, v107
	s_nop 0
	v_exp_f32_e32 v108, v108
	v_exp_f32_e32 v109, v109
	v_exp_f32_e32 v110, v110
	s_nop 0
	v_exp_f32_e32 v111, v111
	v_exp_f32_e32 v112, v112
	v_exp_f32_e32 v113, v113
	s_lshl_b32 s4, s4, 9
	s_lshl_b32 s5, s5, 7
	s_or_b32 s4, s4, s5
	v_or_b32_e32 v66, v66, v68
	s_ashr_i32 s5, s4, 31
	v_mov_b32_e32 v166, v188
	v_mov_b32_e32 v167, v189
	v_lshl_add_u64 v[188:189], v[66:67], 0, s[4:5]
	v_mov_b64_e32 v[32:33], v[16:17]
	v_mov_b64_e32 v[48:49], v[16:17]
	v_mov_b64_e32 v[80:81], v[16:17]
	v_mov_b32_e32 v172, v192
	v_mov_b32_e32 v173, v193
	v_lshl_add_u64 v[192:193], s[34:35], 0, v[186:187]
	v_mov_b32_e32 v195, 0
	s_mov_b32 s5, 0x8000
	s_movk_i32 s4, 0x4000
	s_mov_b32 s34, -1
	v_mov_b64_e32 v[30:31], v[14:15]
	v_mov_b64_e32 v[28:29], v[12:13]
	v_mov_b64_e32 v[26:27], v[10:11]
	v_mov_b64_e32 v[24:25], v[8:9]
	v_mov_b64_e32 v[22:23], v[6:7]
	v_mov_b64_e32 v[20:21], v[4:5]
	v_mov_b64_e32 v[18:19], v[2:3]
	v_mov_b64_e32 v[46:47], v[14:15]
	v_mov_b64_e32 v[44:45], v[12:13]
	v_mov_b64_e32 v[42:43], v[10:11]
	v_mov_b64_e32 v[40:41], v[8:9]
	v_mov_b64_e32 v[38:39], v[6:7]
	v_mov_b64_e32 v[36:37], v[4:5]
	v_mov_b64_e32 v[34:35], v[2:3]
	v_mov_b64_e32 v[78:79], v[14:15]
	v_mov_b64_e32 v[76:77], v[12:13]
	v_mov_b64_e32 v[74:75], v[10:11]
	v_mov_b64_e32 v[72:73], v[8:9]
	v_mov_b64_e32 v[70:71], v[6:7]
	v_mov_b64_e32 v[68:69], v[4:5]
	v_mov_b64_e32 v[66:67], v[2:3]
	v_add_u32_e32 v188, 0x1de1d800, v188
	v_add_u32_e32 v192, 0x1cdfd800, v192
	v_add_u32_e32 v189, 0x10000, v188
	s_add_u32 s98, s72, 0x2a302800
	s_addc_u32 s99, s73, 0
	s_waitcnt lgkmcnt(0)
	s_barrier
.LBB0_710:
	s_mov_b32 s35, s4
	s_mov_b32 s4, s52
	global_load_dwordx4 v[204:207], v192, s[98:99] offset:128
	global_load_dwordx4 v[208:211], v188, s[98:99]
	global_load_dwordx2 v[218:219], v214, s[98:99] offset:-2048
	ds_read_b128 v[118:121], v199 offset:17424
	ds_read_b128 v[114:117], v199 offset:17408
	ds_read_b128 v[130:133], v199 offset:22016
	ds_read_b128 v[134:137], v199 offset:22032
	ds_read_b128 v[156:159], v199 offset:17488
	ds_read_b128 v[238:241], v199 offset:17472
	s_waitcnt lgkmcnt(4)
	v_add_f32_e32 v160, v86, v82
	v_mfma_scale_f32_32x32x64_f8f6f4 v[114:129], v[114:119], v[168:173], v[50:65], v120, v194 op_sel_hi:[0,0,0] cbsz:2 blgp:2
	v_cvt_pk_fp8_f32 v154, v82, v83
	v_cvt_pk_fp8_f32 v155, v98, v99
	v_cvt_pk_fp8_f32 v154, v84, v85 op_sel:[0,0,1]
	v_cvt_pk_fp8_f32 v155, v100, v101 op_sel:[0,0,1]
	v_add_f32_e32 v82, v87, v83
	v_add_f32_e32 v83, v88, v84
	v_permlane32_swap_b32_e32 v154, v155
	ds_read_b128 v[244:247], v199 offset:22080
	ds_read_b128 v[248:251], v199 offset:22096
	s_waitcnt lgkmcnt(3)
	v_mfma_scale_f32_32x32x64_f8f6f4 v[130:145], v[130:135], v[168:173], v[50:65], v136, v194 op_sel_hi:[0,0,0] cbsz:2 blgp:2
	v_add_f32_e32 v84, v89, v85
	v_add_f32_e32 v85, v90, v160
	v_add_f32_e32 v82, v91, v82
	v_mov_b32_e32 v242, v156
	v_mov_b32_e32 v243, v157
	v_add_f32_e32 v83, v92, v83
	v_add_f32_e32 v84, v93, v84
	v_add_f32_e32 v159, v94, v85
	v_add_f32_e32 v160, v95, v82
	v_add_f32_e32 v161, v96, v83
	v_add_f32_e32 v186, v97, v84
	ds_read_b128 v[230:233], v222 offset:5120
	ds_read_b128 v[234:237], v222 offset:5136
	s_waitcnt lgkmcnt(4)
	v_mfma_scale_f32_32x32x64_f8f6f4 v[114:129], v[238:243], v[162:167], v[114:129], v158, v190 op_sel_hi:[0,0,0] cbsz:2 blgp:2
	v_cvt_pk_fp8_f32 v156, v86, v87
	v_cvt_pk_fp8_f32 v157, v102, v103
	v_cvt_pk_fp8_f32 v156, v88, v89 op_sel:[0,0,1]
	v_cvt_pk_fp8_f32 v157, v104, v105 op_sel:[0,0,1]
	v_add_f32_e32 v98, v98, v159
	v_add_f32_e32 v99, v99, v160
	v_permlane32_swap_b32_e32 v156, v157
	v_add_f32_e32 v100, v100, v161
	v_add_f32_e32 v101, v101, v186
	v_add_f32_e32 v98, v102, v98
	ds_read_b128 v[82:85], v222 offset:7680
	ds_read_b128 v[86:89], v222 offset:7696
	s_waitcnt lgkmcnt(4)
	v_mfma_scale_f32_32x32x64_f8f6f4 v[130:145], v[244:249], v[162:167], v[130:145], v250, v190 op_sel_hi:[0,0,0] cbsz:2 blgp:2
	v_cvt_pk_fp8_f32 v158, v90, v91
	v_cvt_pk_fp8_f32 v159, v106, v107
	v_cvt_pk_fp8_f32 v158, v92, v93 op_sel:[0,0,1]
	v_cvt_pk_fp8_f32 v159, v108, v109 op_sel:[0,0,1]
	v_add_f32_e32 v90, v103, v99
	v_add_f32_e32 v91, v104, v100
	v_permlane32_swap_b32_e32 v158, v159
	s_waitcnt lgkmcnt(2)
	v_mfma_scale_f32_32x32x64_f8f6f4 v[114:129], v[230:237], v[146:153], v[114:129], v220, v1 op_sel_hi:[0,0,0]
	v_add_f32_e32 v92, v105, v101
	v_add_f32_e32 v93, v106, v98
	v_add_f32_e32 v90, v107, v90
	s_waitcnt lgkmcnt(0)
	v_mfma_scale_f32_32x32x64_f8f6f4 v[130:145], v[82:89], v[146:153], v[130:145], v220, v1 op_sel_hi:[0,0,0]
	v_add_f32_e32 v91, v108, v91
	v_add_f32_e32 v92, v109, v92
	v_add_f32_e32 v93, v110, v93
	v_add_f32_e32 v90, v111, v90
	v_add_f32_e32 v91, v112, v91
	v_add_f32_e32 v92, v113, v92
	v_cvt_pk_fp8_f32 v160, v94, v95
	v_cvt_pk_fp8_f32 v161, v110, v111
	v_cvt_pk_fp8_f32 v160, v96, v97 op_sel:[0,0,1]
	v_cvt_pk_fp8_f32 v161, v112, v113 op_sel:[0,0,1]
	v_add_f32_e32 v82, v93, v90
	v_add_f32_e32 v83, v91, v92
	v_permlane32_swap_b32_e32 v160, v161
	v_add_f32_e32 v229, v82, v83
	v_mov_b32_e32 v230, v229
	v_add_u32_e32 v82, s5, v224
	s_waitcnt vmcnt(0)
	ds_write_b128 v82, v[204:207]
	ds_write_b128 v225, v[208:211] offset:49152
	ds_write_b64 v226, v[218:219]
	v_add_u32_e32 v98, s4, v191
	ds_read_b128 v[90:93], v98
	ds_read_b128 v[94:97], v98 offset:16
	v_max3_f32 v82, v114, s88, v115
	v_max3_f32 v82, v82, v116, v117
	v_max3_f32 v82, v82, v118, v119
	v_permlane32_swap_b32_e32 v229, v230
	v_max3_f32 v99, v82, v120, v121
	ds_read_b128 v[82:85], v98 offset:2560
	ds_read_b128 v[86:89], v98 offset:2576
	v_max3_f32 v99, v99, v122, v123
	v_max3_f32 v99, v99, v124, v125
	v_max3_f32 v99, v99, v126, v127
	v_max3_f32 v99, v99, v128, v129
	v_max3_f32 v99, v99, v130, v131
	v_max3_f32 v99, v99, v132, v133
	v_max3_f32 v99, v99, v134, v135
	v_max3_f32 v99, v99, v136, v137
	v_max3_f32 v99, v99, v138, v139
	v_max3_f32 v99, v99, v140, v141
	v_max3_f32 v99, v99, v142, v143
	v_max3_f32 v99, v99, v144, v145
	v_mov_b32_e32 v100, v99
	v_mov_b32_e32 v186, 1.0
	s_nop 0
	v_permlane32_swap_b32_e32 v99, v100
	v_max_f32_e32 v99, v99, v100
	v_cmp_ge_f32_e32 vcc, s89, v99
	s_cmp_eq_u64 vcc, exec
	s_cbranch_scc1 .LBB0_712
	v_add_f32_e32 v99, -4.0, v99
	v_max_f32_e32 v99, 0, v99
	v_exp_f32_e64 v186, -v99
	v_sub_f32_e32 v129, v129, v99
	v_sub_f32_e32 v128, v128, v99
	v_sub_f32_e32 v127, v127, v99
	v_sub_f32_e32 v126, v126, v99
	v_sub_f32_e32 v125, v125, v99
	v_sub_f32_e32 v124, v124, v99
	v_sub_f32_e32 v123, v123, v99
	v_sub_f32_e32 v122, v122, v99
	v_sub_f32_e32 v121, v121, v99
	v_sub_f32_e32 v120, v120, v99
	v_sub_f32_e32 v119, v119, v99
	v_sub_f32_e32 v118, v118, v99
	v_sub_f32_e32 v117, v117, v99
	v_sub_f32_e32 v116, v116, v99
	v_sub_f32_e32 v115, v115, v99
	v_sub_f32_e32 v114, v114, v99
	v_sub_f32_e32 v145, v145, v99
	v_sub_f32_e32 v144, v144, v99
	v_sub_f32_e32 v143, v143, v99
	v_sub_f32_e32 v142, v142, v99
	v_sub_f32_e32 v141, v141, v99
	v_sub_f32_e32 v140, v140, v99
	v_sub_f32_e32 v139, v139, v99
	v_sub_f32_e32 v138, v138, v99
	v_sub_f32_e32 v137, v137, v99
	v_sub_f32_e32 v136, v136, v99
	v_sub_f32_e32 v135, v135, v99
	v_sub_f32_e32 v134, v134, v99
	v_sub_f32_e32 v133, v133, v99
	v_sub_f32_e32 v132, v132, v99
	v_sub_f32_e32 v131, v131, v99
	v_sub_f32_e32 v130, v130, v99
	v_sub_f32_e32 v65, v65, v99
	v_sub_f32_e32 v64, v64, v99
	v_sub_f32_e32 v63, v63, v99
	v_sub_f32_e32 v62, v62, v99
	v_sub_f32_e32 v61, v61, v99
	v_sub_f32_e32 v60, v60, v99
	v_sub_f32_e32 v59, v59, v99
	v_sub_f32_e32 v58, v58, v99
	v_sub_f32_e32 v57, v57, v99
	v_sub_f32_e32 v56, v56, v99
	v_sub_f32_e32 v55, v55, v99
	v_sub_f32_e32 v54, v54, v99
	v_sub_f32_e32 v53, v53, v99
	v_sub_f32_e32 v52, v52, v99
	v_sub_f32_e32 v51, v51, v99
	v_sub_f32_e32 v50, v50, v99
.LBB0_712:
	s_waitcnt lgkmcnt(2)
	v_mfma_scale_f32_32x32x64_f8f6f4 v[66:81], v[90:97], v[154:161], v[66:81], v220, v220 op_sel_hi:[0,0,0]
	s_waitcnt lgkmcnt(0)
	v_mfma_scale_f32_32x32x64_f8f6f4 v[34:49], v[82:89], v[154:161], v[34:49], v220, v220 op_sel_hi:[0,0,0]
	ds_read_b128 v[82:85], v98 offset:5120
	ds_read_b128 v[86:89], v98 offset:5136
	v_exp_f32_e32 v114, v114
	v_exp_f32_e32 v115, v115
	v_exp_f32_e32 v116, v116
	v_exp_f32_e32 v117, v117
	v_exp_f32_e32 v118, v118
	v_exp_f32_e32 v119, v119
	v_exp_f32_e32 v120, v120
	v_exp_f32_e32 v121, v121
	s_waitcnt lgkmcnt(0)
	v_mfma_scale_f32_32x32x64_f8f6f4 v[18:33], v[82:89], v[154:161], v[18:33], v220, v220 op_sel_hi:[0,0,0]
	v_exp_f32_e32 v122, v122
	v_exp_f32_e32 v123, v123
	v_exp_f32_e32 v124, v124
	ds_read_b128 v[82:85], v98 offset:7680
	ds_read_b128 v[86:89], v98 offset:7696
	v_exp_f32_e32 v125, v125
	v_exp_f32_e32 v126, v126
	v_exp_f32_e32 v127, v127
	v_exp_f32_e32 v128, v128
	v_exp_f32_e32 v129, v129
	v_exp_f32_e32 v130, v130
	v_exp_f32_e32 v131, v131
	v_exp_f32_e32 v132, v132
	v_exp_f32_e32 v133, v133
	s_waitcnt lgkmcnt(0)
	v_mfma_scale_f32_32x32x64_f8f6f4 v[2:17], v[82:89], v[154:161], v[2:17], v220, v220 op_sel_hi:[0,0,0]
	v_exp_f32_e32 v134, v134
	v_exp_f32_e32 v135, v135
	v_exp_f32_e32 v136, v136
	v_exp_f32_e32 v137, v137
	v_exp_f32_e32 v138, v138
	v_exp_f32_e32 v139, v139
	v_exp_f32_e32 v140, v140
	v_exp_f32_e32 v141, v141
	v_exp_f32_e32 v142, v142
	v_exp_f32_e32 v143, v143
	v_exp_f32_e32 v144, v144
	v_exp_f32_e32 v145, v145
	v_cmp_gt_f32_e32 vcc, 1.0, v186
	s_cbranch_vccz .LBB0_714
	v_pk_mul_f32 v[80:81], v[80:81], v[186:187] op_sel_hi:[1,0]
	v_pk_mul_f32 v[78:79], v[78:79], v[186:187] op_sel_hi:[1,0]
	v_pk_mul_f32 v[76:77], v[76:77], v[186:187] op_sel_hi:[1,0]
	v_pk_mul_f32 v[74:75], v[74:75], v[186:187] op_sel_hi:[1,0]
	v_pk_mul_f32 v[72:73], v[72:73], v[186:187] op_sel_hi:[1,0]
	v_pk_mul_f32 v[70:71], v[70:71], v[186:187] op_sel_hi:[1,0]
	v_pk_mul_f32 v[68:69], v[68:69], v[186:187] op_sel_hi:[1,0]
	v_pk_mul_f32 v[66:67], v[66:67], v[186:187] op_sel_hi:[1,0]
	v_pk_mul_f32 v[48:49], v[48:49], v[186:187] op_sel_hi:[1,0]
	v_pk_mul_f32 v[46:47], v[46:47], v[186:187] op_sel_hi:[1,0]
	v_pk_mul_f32 v[44:45], v[44:45], v[186:187] op_sel_hi:[1,0]
	v_pk_mul_f32 v[42:43], v[42:43], v[186:187] op_sel_hi:[1,0]
	v_pk_mul_f32 v[40:41], v[40:41], v[186:187] op_sel_hi:[1,0]
	v_pk_mul_f32 v[38:39], v[38:39], v[186:187] op_sel_hi:[1,0]
	v_pk_mul_f32 v[36:37], v[36:37], v[186:187] op_sel_hi:[1,0]
	v_pk_mul_f32 v[34:35], v[34:35], v[186:187] op_sel_hi:[1,0]
	v_pk_mul_f32 v[32:33], v[186:187], v[32:33] op_sel_hi:[0,1]
	v_pk_mul_f32 v[30:31], v[186:187], v[30:31] op_sel_hi:[0,1]
	v_pk_mul_f32 v[28:29], v[186:187], v[28:29] op_sel_hi:[0,1]
	v_pk_mul_f32 v[26:27], v[186:187], v[26:27] op_sel_hi:[0,1]
	v_pk_mul_f32 v[24:25], v[186:187], v[24:25] op_sel_hi:[0,1]
	v_pk_mul_f32 v[22:23], v[186:187], v[22:23] op_sel_hi:[0,1]
	v_pk_mul_f32 v[20:21], v[186:187], v[20:21] op_sel_hi:[0,1]
	v_pk_mul_f32 v[18:19], v[186:187], v[18:19] op_sel_hi:[0,1]
	v_pk_mul_f32 v[16:17], v[186:187], v[16:17] op_sel_hi:[0,1]
	v_pk_mul_f32 v[14:15], v[186:187], v[14:15] op_sel_hi:[0,1]
	v_pk_mul_f32 v[12:13], v[186:187], v[12:13] op_sel_hi:[0,1]
	v_pk_mul_f32 v[10:11], v[186:187], v[10:11] op_sel_hi:[0,1]
	v_pk_mul_f32 v[8:9], v[186:187], v[8:9] op_sel_hi:[0,1]
	v_pk_mul_f32 v[6:7], v[186:187], v[6:7] op_sel_hi:[0,1]
	v_pk_mul_f32 v[4:5], v[186:187], v[4:5] op_sel_hi:[0,1]
	v_pk_mul_f32 v[2:3], v[186:187], v[2:3] op_sel_hi:[0,1]
.LBB0_714:
	s_barrier
	global_load_dwordx4 v[204:207], v192, s[98:99] offset:192
	global_load_dwordx4 v[208:211], v189, s[98:99]
	global_load_dwordx2 v[196:197], v214, s[98:99] offset:2048
	ds_read_b128 v[86:89], v223 offset:49168
	ds_read_b128 v[82:85], v223 offset:49152
	ds_read_b128 v[98:101], v223 offset:53760
	ds_read_b128 v[102:105], v223 offset:53776
	ds_read_b128 v[156:159], v223 offset:49232
	ds_read_b128 v[240:243], v223 offset:49216
	s_waitcnt lgkmcnt(4)
	v_add_f32_e32 v160, v118, v114
	v_mfma_scale_f32_32x32x64_f8f6f4 v[82:97], v[82:87], v[174:179], v[50:65], v88, v198 op_sel_hi:[0,0,0] cbsz:2 blgp:2
	v_cvt_pk_fp8_f32 v154, v114, v115
	v_cvt_pk_fp8_f32 v155, v130, v131
	v_cvt_pk_fp8_f32 v154, v116, v117 op_sel:[0,0,1]
	v_cvt_pk_fp8_f32 v155, v132, v133 op_sel:[0,0,1]
	v_add_f32_e32 v114, v119, v115
	v_add_f32_e32 v115, v120, v116
	v_permlane32_swap_b32_e32 v154, v155
	ds_read_b128 v[246:249], v223 offset:53824
	ds_read_b128 v[216:219], v223 offset:53840
	s_waitcnt lgkmcnt(3)
	v_mfma_scale_f32_32x32x64_f8f6f4 v[98:113], v[98:103], v[174:179], v[50:65], v104, v198 op_sel_hi:[0,0,0] cbsz:2 blgp:2
	v_add_f32_e32 v116, v121, v117
	v_add_f32_e32 v117, v122, v160
	v_add_f32_e32 v114, v123, v114
	v_mov_b32_e32 v244, v156
	v_mov_b32_e32 v245, v157
	v_add_f32_e32 v115, v124, v115
	v_add_f32_e32 v116, v125, v116
	v_add_f32_e32 v159, v126, v117
	v_add_f32_e32 v160, v127, v114
	v_add_f32_e32 v161, v128, v115
	v_add_f32_e32 v200, v129, v116
	ds_read_b128 v[232:235], v222
	ds_read_b128 v[236:239], v222 offset:16
	s_waitcnt lgkmcnt(4)
	v_mfma_scale_f32_32x32x64_f8f6f4 v[82:97], v[240:245], v[180:185], v[82:97], v158, v202 op_sel_hi:[0,0,0] cbsz:2 blgp:2
	v_cvt_pk_fp8_f32 v156, v118, v119
	v_cvt_pk_fp8_f32 v157, v134, v135
	v_cvt_pk_fp8_f32 v156, v120, v121 op_sel:[0,0,1]
	v_cvt_pk_fp8_f32 v157, v136, v137 op_sel:[0,0,1]
	v_add_f32_e32 v130, v130, v159
	v_add_f32_e32 v131, v131, v160
	v_permlane32_swap_b32_e32 v156, v157
	s_waitcnt lgkmcnt(2)
	v_mov_b32_e32 v250, v216
	v_mov_b32_e32 v251, v217
	v_add_f32_e32 v132, v132, v161
	v_add_f32_e32 v133, v133, v200
	v_add_f32_e32 v130, v134, v130
	ds_read_b128 v[114:117], v222 offset:2560
	ds_read_b128 v[118:121], v222 offset:2576
	v_mfma_scale_f32_32x32x64_f8f6f4 v[98:113], v[246:251], v[180:185], v[98:113], v218, v202 op_sel_hi:[0,0,0] cbsz:2 blgp:2
	v_cvt_pk_fp8_f32 v158, v122, v123
	v_cvt_pk_fp8_f32 v159, v138, v139
	v_cvt_pk_fp8_f32 v158, v124, v125 op_sel:[0,0,1]
	v_cvt_pk_fp8_f32 v159, v140, v141 op_sel:[0,0,1]
	v_add_f32_e32 v122, v135, v131
	v_add_f32_e32 v123, v136, v132
	v_permlane32_swap_b32_e32 v158, v159
	s_waitcnt lgkmcnt(2)
	v_mfma_scale_f32_32x32x64_f8f6f4 v[82:97], v[232:239], v[146:153], v[82:97], v220, v1 op_sel_hi:[0,0,0]
	v_add_f32_e32 v124, v137, v133
	v_add_f32_e32 v125, v138, v130
	v_add_f32_e32 v122, v139, v122
	s_waitcnt lgkmcnt(0)
	v_mfma_scale_f32_32x32x64_f8f6f4 v[98:113], v[114:121], v[146:153], v[98:113], v220, v1 op_sel_hi:[0,0,0]
	v_add_f32_e32 v123, v140, v123
	v_add_f32_e32 v124, v141, v124
	v_add_f32_e32 v125, v142, v125
	v_add_f32_e32 v122, v143, v122
	v_add_f32_e32 v123, v144, v123
	v_add_f32_e32 v124, v145, v124
	v_cvt_pk_fp8_f32 v160, v126, v127
	v_cvt_pk_fp8_f32 v161, v142, v143
	v_cvt_pk_fp8_f32 v160, v128, v129 op_sel:[0,0,1]
	v_cvt_pk_fp8_f32 v161, v144, v145 op_sel:[0,0,1]
	v_add_f32_e32 v114, v125, v122
	v_add_f32_e32 v115, v123, v124
	v_permlane32_swap_b32_e32 v160, v161
	v_add_f32_e32 v130, v114, v115
	v_mov_b32_e32 v131, v130
	v_add_u32_e32 v114, s4, v224
	s_waitcnt vmcnt(0)
	ds_write_b128 v114, v[204:207]
	ds_write_b128 v203, v[208:211]
	ds_write_b64 v227, v[196:197]
	v_add_u32_e32 v132, s35, v191
	ds_read_b128 v[122:125], v132
	ds_read_b128 v[126:129], v132 offset:16
	v_max3_f32 v114, v82, s88, v83
	v_max3_f32 v114, v114, v84, v85
	v_max3_f32 v114, v114, v86, v87
	v_permlane32_swap_b32_e32 v130, v131
	v_max3_f32 v133, v114, v88, v89
	ds_read_b128 v[114:117], v132 offset:2560
	ds_read_b128 v[118:121], v132 offset:2576
	v_max3_f32 v133, v133, v90, v91
	v_max3_f32 v133, v133, v92, v93
	v_max3_f32 v133, v133, v94, v95
	v_max3_f32 v133, v133, v96, v97
	v_max3_f32 v133, v133, v98, v99
	v_max3_f32 v133, v133, v100, v101
	v_max3_f32 v133, v133, v102, v103
	v_max3_f32 v133, v133, v104, v105
	v_max3_f32 v133, v133, v106, v107
	v_max3_f32 v133, v133, v108, v109
	v_max3_f32 v133, v133, v110, v111
	v_max3_f32 v133, v133, v112, v113
	v_mov_b32_e32 v134, v133
	v_mov_b32_e32 v138, 1.0
	s_nop 0
	v_permlane32_swap_b32_e32 v133, v134
	v_max_f32_e32 v133, v133, v134
	v_cmp_ge_f32_e32 vcc, s89, v133
	s_cmp_eq_u64 vcc, exec
	s_cbranch_scc1 .LBB0_716
	v_add_f32_e32 v133, -4.0, v133
	v_max_f32_e32 v133, 0, v133
	v_exp_f32_e64 v138, -v133
	v_sub_f32_e32 v97, v97, v133
	v_sub_f32_e32 v96, v96, v133
	v_sub_f32_e32 v95, v95, v133
	v_sub_f32_e32 v94, v94, v133
	v_sub_f32_e32 v93, v93, v133
	v_sub_f32_e32 v92, v92, v133
	v_sub_f32_e32 v91, v91, v133
	v_sub_f32_e32 v90, v90, v133
	v_sub_f32_e32 v89, v89, v133
	v_sub_f32_e32 v88, v88, v133
	v_sub_f32_e32 v87, v87, v133
	v_sub_f32_e32 v86, v86, v133
	v_sub_f32_e32 v85, v85, v133
	v_sub_f32_e32 v84, v84, v133
	v_sub_f32_e32 v83, v83, v133
	v_sub_f32_e32 v82, v82, v133
	v_sub_f32_e32 v113, v113, v133
	v_sub_f32_e32 v112, v112, v133
	v_sub_f32_e32 v111, v111, v133
	v_sub_f32_e32 v110, v110, v133
	v_sub_f32_e32 v109, v109, v133
	v_sub_f32_e32 v108, v108, v133
	v_sub_f32_e32 v107, v107, v133
	v_sub_f32_e32 v106, v106, v133
	v_sub_f32_e32 v105, v105, v133
	v_sub_f32_e32 v104, v104, v133
	v_sub_f32_e32 v103, v103, v133
	v_sub_f32_e32 v102, v102, v133
	v_sub_f32_e32 v101, v101, v133
	v_sub_f32_e32 v100, v100, v133
	v_sub_f32_e32 v99, v99, v133
	v_sub_f32_e32 v98, v98, v133
	v_sub_f32_e32 v65, v65, v133
	v_sub_f32_e32 v64, v64, v133
	v_sub_f32_e32 v63, v63, v133
	v_sub_f32_e32 v62, v62, v133
	v_sub_f32_e32 v61, v61, v133
	v_sub_f32_e32 v60, v60, v133
	v_sub_f32_e32 v59, v59, v133
	v_sub_f32_e32 v58, v58, v133
	v_sub_f32_e32 v57, v57, v133
	v_sub_f32_e32 v56, v56, v133
	v_sub_f32_e32 v55, v55, v133
	v_sub_f32_e32 v54, v54, v133
	v_sub_f32_e32 v53, v53, v133
	v_sub_f32_e32 v52, v52, v133
	v_sub_f32_e32 v51, v51, v133
	v_sub_f32_e32 v50, v50, v133
.LBB0_716:
	s_waitcnt lgkmcnt(2)
	v_mfma_scale_f32_32x32x64_f8f6f4 v[66:81], v[122:129], v[154:161], v[66:81], v220, v220 op_sel_hi:[0,0,0]
	s_waitcnt lgkmcnt(0)
	v_mfma_scale_f32_32x32x64_f8f6f4 v[34:49], v[114:121], v[154:161], v[34:49], v220, v220 op_sel_hi:[0,0,0]
	ds_read_b128 v[114:117], v132 offset:5120
	ds_read_b128 v[118:121], v132 offset:5136
	v_exp_f32_e32 v82, v82
	v_exp_f32_e32 v83, v83
	v_exp_f32_e32 v84, v84
	v_exp_f32_e32 v85, v85
	v_exp_f32_e32 v86, v86
	v_exp_f32_e32 v87, v87
	v_exp_f32_e32 v88, v88
	v_exp_f32_e32 v89, v89
	s_waitcnt lgkmcnt(0)
	v_mfma_scale_f32_32x32x64_f8f6f4 v[18:33], v[114:121], v[154:161], v[18:33], v220, v220 op_sel_hi:[0,0,0]
	v_exp_f32_e32 v90, v90
	v_exp_f32_e32 v91, v91
	v_exp_f32_e32 v92, v92
	ds_read_b128 v[114:117], v132 offset:7680
	ds_read_b128 v[118:121], v132 offset:7696
	v_exp_f32_e32 v93, v93
	v_exp_f32_e32 v94, v94
	v_exp_f32_e32 v95, v95
	v_exp_f32_e32 v96, v96
	v_exp_f32_e32 v97, v97
	v_exp_f32_e32 v98, v98
	v_exp_f32_e32 v99, v99
	v_exp_f32_e32 v100, v100
	v_exp_f32_e32 v101, v101
	s_waitcnt lgkmcnt(0)
	v_mfma_scale_f32_32x32x64_f8f6f4 v[2:17], v[114:121], v[154:161], v[2:17], v220, v220 op_sel_hi:[0,0,0]
	v_exp_f32_e32 v102, v102
	v_exp_f32_e32 v103, v103
	v_exp_f32_e32 v104, v104
	v_exp_f32_e32 v105, v105
	v_exp_f32_e32 v106, v106
	v_exp_f32_e32 v107, v107
	v_exp_f32_e32 v108, v108
	v_exp_f32_e32 v109, v109
	v_exp_f32_e32 v110, v110
	v_exp_f32_e32 v111, v111
	v_exp_f32_e32 v112, v112
	v_exp_f32_e32 v113, v113
	v_cmp_gt_f32_e32 vcc, 1.0, v138
	s_cbranch_vccz .LBB0_718
	v_pk_mul_f32 v[80:81], v[80:81], v[138:139] op_sel_hi:[1,0]
	v_pk_mul_f32 v[78:79], v[78:79], v[138:139] op_sel_hi:[1,0]
	v_pk_mul_f32 v[76:77], v[76:77], v[138:139] op_sel_hi:[1,0]
	v_pk_mul_f32 v[74:75], v[74:75], v[138:139] op_sel_hi:[1,0]
	v_pk_mul_f32 v[72:73], v[72:73], v[138:139] op_sel_hi:[1,0]
	v_pk_mul_f32 v[70:71], v[70:71], v[138:139] op_sel_hi:[1,0]
	v_pk_mul_f32 v[68:69], v[68:69], v[138:139] op_sel_hi:[1,0]
	v_pk_mul_f32 v[66:67], v[66:67], v[138:139] op_sel_hi:[1,0]
	v_pk_mul_f32 v[48:49], v[48:49], v[138:139] op_sel_hi:[1,0]
	v_pk_mul_f32 v[46:47], v[46:47], v[138:139] op_sel_hi:[1,0]
	v_pk_mul_f32 v[44:45], v[44:45], v[138:139] op_sel_hi:[1,0]
	v_pk_mul_f32 v[42:43], v[42:43], v[138:139] op_sel_hi:[1,0]
	v_pk_mul_f32 v[40:41], v[40:41], v[138:139] op_sel_hi:[1,0]
	v_pk_mul_f32 v[38:39], v[38:39], v[138:139] op_sel_hi:[1,0]
	v_pk_mul_f32 v[36:37], v[36:37], v[138:139] op_sel_hi:[1,0]
	v_pk_mul_f32 v[34:35], v[34:35], v[138:139] op_sel_hi:[1,0]
	v_pk_mul_f32 v[32:33], v[138:139], v[32:33] op_sel_hi:[0,1]
	v_pk_mul_f32 v[30:31], v[138:139], v[30:31] op_sel_hi:[0,1]
	v_pk_mul_f32 v[28:29], v[138:139], v[28:29] op_sel_hi:[0,1]
	v_pk_mul_f32 v[26:27], v[138:139], v[26:27] op_sel_hi:[0,1]
	v_pk_mul_f32 v[24:25], v[138:139], v[24:25] op_sel_hi:[0,1]
	v_pk_mul_f32 v[22:23], v[138:139], v[22:23] op_sel_hi:[0,1]
	v_pk_mul_f32 v[20:21], v[138:139], v[20:21] op_sel_hi:[0,1]
	v_pk_mul_f32 v[18:19], v[138:139], v[18:19] op_sel_hi:[0,1]
	v_pk_mul_f32 v[16:17], v[138:139], v[16:17] op_sel_hi:[0,1]
	v_pk_mul_f32 v[14:15], v[138:139], v[14:15] op_sel_hi:[0,1]
	v_pk_mul_f32 v[12:13], v[138:139], v[12:13] op_sel_hi:[0,1]
	v_pk_mul_f32 v[10:11], v[138:139], v[10:11] op_sel_hi:[0,1]
	v_pk_mul_f32 v[8:9], v[138:139], v[8:9] op_sel_hi:[0,1]
	v_pk_mul_f32 v[6:7], v[138:139], v[6:7] op_sel_hi:[0,1]
	v_pk_mul_f32 v[4:5], v[138:139], v[4:5] op_sel_hi:[0,1]
	v_pk_mul_f32 v[2:3], v[138:139], v[2:3] op_sel_hi:[0,1]
.LBB0_718:
	v_add_f32_e32 v114, v229, v230
	v_add_u32_e32 v188, 0x20000, v188
	v_add_u32_e32 v189, 0x20000, v189
	v_fmac_f32_e32 v114, v195, v228
	v_add_f32_e32 v195, v130, v131
	s_add_i32 s34, s34, 2
	v_add_u32_e32 v192, 0x80, v192
	v_fmac_f32_e32 v195, v114, v186
	s_cmpk_gt_u32 s34, 0xfc
	v_add_u32_e32 v214, 0x2000, v214
	s_barrier
	s_cbranch_scc1 .LBB0_720
	s_mov_b32 s52, s5
	s_mov_b32 s5, s35
	v_mov_b32_e32 v228, v138
	s_branch .LBB0_710

.LBB0_1731:
	s_mov_b64 s[4:5], -1
	s_and_b64 vcc, exec, s[8:9]
	s_cbranch_vccz .LBB0_1715
	s_ashr_i32 s4, s16, 31
	s_lshr_b32 s4, s4, 24
	s_add_i32 s5, s16, s4
	s_ashr_i32 s4, s5, 8
	s_and_b32 s5, s5, 0xffffff00
	s_sub_i32 s8, s16, s5
	s_lshl_b32 s9, s4, 2
	s_bfe_u32 s5, s8, 0x20001
	s_or_b32 s46, s5, s9
	s_ashr_i32 s9, s8, 3
	s_lshl_b32 s8, s8, 5
	s_and_b32 s8, s8, 32
	s_add_i32 s48, s8, s9
	s_ashr_i32 s49, s48, 31
	s_mul_i32 s9, s48, 0xc0000
	s_mul_hi_i32 s8, s48, 0xc0000
	s_add_u32 s10, s24, s9
	s_addc_u32 s11, s25, s8
	s_mul_i32 s8, s46, 0xc0
	s_ashr_i32 s9, s8, 31
	s_lshl_b64 s[8:9], s[8:9], 1
	s_add_u32 s10, s10, s8
	v_mov_b32_e32 v4, v0
	s_addc_u32 s11, s11, s9
	s_movk_i32 s14, 0xffe0
	v_ashrrev_i32_e32 v2, 1, v4
	v_bfe_u32 v221, v4, 5, 1
	v_bfi_b32 v212, s14, v2, v4
	v_mov_b64_e32 v[2:3], s[10:11]
	s_movk_i32 s10, 0xc00
	v_mad_i64_i32 v[2:3], s[10:11], v212, s10, v[2:3]
	v_lshlrev_b32_e32 v186, 5, v221
	s_lshl_b32 s52, s46, 7
	v_and_b32_e32 v18, 31, v4
	v_lshl_add_u64 v[10:11], v[2:3], 0, v[186:187]
	v_lshlrev_b32_e32 v2, 3, v4
	s_ashr_i32 s53, s52, 31
	v_and_b32_e32 v90, 56, v2
	v_mul_u32_u24_e32 v2, 0x90, v18
	s_add_u32 s12, s28, s52
	v_add3_u32 v223, 0, v2, v186
	v_mov_b32_e32 v2, s84
	s_addc_u32 s13, s29, s53
	s_ashr_i32 s47, s46, 31
	v_ashrrev_i32_e32 v12, 3, v4
	v_mad_u32_u24 v2, v18, s85, v2
	s_lshl_b64 s[54:55], s[46:47], 21
	v_add_u32_e32 v222, v2, v186
	v_lshlrev_b32_e32 v2, 4, v4
	v_ashrrev_i32_e32 v13, 31, v12
	s_add_u32 s8, s40, s54
	v_ashrrev_i32_e32 v19, 2, v4
	v_and_b32_e32 v20, 48, v2
	v_lshlrev_b64 v[66:67], 10, v[12:13]
	s_addc_u32 s9, s41, s55
	v_lshl_or_b32 v186, v19, 14, v20
	v_lshl_add_u64 v[2:3], s[12:13], 0, v[66:67]
	v_lshlrev_b32_e32 v68, 1, v90
	v_mov_b32_e32 v69, v187
	v_lshl_or_b32 v214, v12, 6, v90
	v_lshl_add_u64 v[14:15], v[2:3], 0, v[68:69]
	global_load_dwordx4 v[2:5], v186, s[8:9]
	global_load_dwordx4 v[6:9], v[14:15], off
	global_load_dwordx2 v[16:17], v214, s[30:31]
	global_load_dwordx4 v[196:199], v[10:11], off offset:336
	s_movk_i32 s10, 0x90
	v_mul_lo_u32 v13, v19, s85
	v_mul_lo_u32 v69, v12, s10
	v_mul_lo_u32 v91, v12, s85
	s_mov_b32 s10, 0x10000
	v_add3_u32 v224, 0, v13, v20
	v_add_u32_e32 v12, 0, v69
	v_add_u32_e32 v13, s84, v91
	global_load_dwordx4 v[150:153], v[10:11], off offset:272
	global_load_dwordx4 v[146:149], v[10:11], off offset:256
	global_load_dwordx4 v[174:177], v[10:11], off offset:320
	global_load_dwordx4 v[200:203], v[10:11], off offset:144
	global_load_dwordx4 v[180:183], v[10:11], off offset:128
	global_load_dwordx4 v[192:195], v[10:11], off offset:16
	global_load_dwordx4 v[168:171], v[10:11], off
	global_load_dwordx4 v[188:191], v[10:11], off offset:80
	global_load_dwordx4 v[162:165], v[10:11], off offset:64
	v_add_co_u32_e32 v10, vcc, s10, v14
	v_add_u32_e32 v225, v12, v68
	v_add_u32_e32 v226, v13, v90
	v_addc_co_u32_e32 v11, vcc, 0, v15, vcc
	s_waitcnt vmcnt(0)
	v_ashrrev_i32_e32 v213, 31, v212
	s_waitcnt vmcnt(0)
	v_add_u32_e32 v199, 0xc000, v223
	v_mov_b32_e32 v215, v187
	ds_write_b128 v224, v[2:5]
	ds_write_b128 v225, v[6:9] offset:49152
	ds_write_b64 v226, v[16:17]
	s_waitcnt lgkmcnt(0)
	s_barrier
	global_load_dwordx4 v[76:79], v186, s[8:9] offset:64
	global_load_dwordx4 v[80:83], v[10:11], off
	global_load_dwordx2 v[88:89], v214, s[34:35]
	v_lshlrev_b32_e32 v2, 6, v18
	ds_read_b128 v[18:21], v223 offset:49152
	ds_read_b128 v[28:31], v223 offset:49168
	ds_read_b128 v[24:27], v223 offset:53760
	ds_read_b128 v[50:53], v223 offset:53776
	ds_read_b128 v[62:65], v223 offset:49232
	ds_read_b128 v[58:61], v223 offset:49216
	s_waitcnt lgkmcnt(4)
	v_mov_b32_e32 v22, v28
	v_mov_b32_e32 v23, v29
	v_mov_b32_e32 v178, v196
	v_mov_b32_e32 v179, v197
	s_mov_b32 s8, 0
	s_mov_b32 s9, s8
	v_mfma_scale_f32_32x32x64_f8f6f4 v[34:49], v[18:23], v[174:179], 0, v30, v198 op_sel_hi:[0,0,0] cbsz:2 blgp:2
	v_sub_u32_e32 v191, v223, v2
	s_mov_b32 s10, s8
	s_mov_b32 s11, s8
	s_mov_b32 s12, s8
	s_mov_b32 s13, s8
	s_mov_b32 s14, s8
	s_mov_b32 s15, s8
	s_mov_b32 s16, s8
	s_mov_b32 s17, s8
	s_mov_b32 s18, s8
	s_mov_b32 s19, s8
	s_mov_b32 s20, s8
	s_mov_b32 s21, s8
	s_mov_b32 s22, s8
	s_mov_b32 s23, s8
	v_mov_b64_e32 v[2:3], s[8:9]
	v_mov_b64_e32 v[4:5], s[10:11]
	v_mov_b64_e32 v[6:7], s[12:13]
	v_mov_b64_e32 v[8:9], s[14:15]
	v_mov_b64_e32 v[10:11], s[16:17]
	v_mov_b64_e32 v[12:13], s[18:19]
	v_mov_b64_e32 v[14:15], s[20:21]
	v_mov_b64_e32 v[16:17], s[22:23]
	s_waitcnt lgkmcnt(2)
	v_mov_b32_e32 v28, v50
	v_mov_b32_e32 v29, v51
	ds_read_b128 v[70:73], v223 offset:53824
	ds_read_b128 v[84:87], v223 offset:53840
	v_mfma_scale_f32_32x32x64_f8f6f4 v[18:33], v[24:29], v[174:179], 0, v52, v198 op_sel_hi:[0,0,0] cbsz:2 blgp:2
	v_mov_b32_e32 v184, v200
	v_mov_b32_e32 v185, v201
	ds_read_b128 v[50:53], v222
	ds_read_b128 v[54:57], v222 offset:16
	s_waitcnt lgkmcnt(4)
	v_mfma_scale_f32_32x32x64_f8f6f4 v[34:49], v[58:63], v[180:185], v[34:49], v64, v202 op_sel_hi:[0,0,0] cbsz:2 blgp:2
	s_waitcnt lgkmcnt(2)
	v_mov_b32_e32 v74, v84
	v_mov_b32_e32 v75, v85
	ds_read_b128 v[58:61], v222 offset:2560
	ds_read_b128 v[62:65], v222 offset:2576
	v_mfma_scale_f32_32x32x64_f8f6f4 v[18:33], v[70:75], v[180:185], v[18:33], v86, v202 op_sel_hi:[0,0,0] cbsz:2 blgp:2
	s_waitcnt lgkmcnt(2)
	v_mfma_scale_f32_32x32x64_f8f6f4 v[34:49], v[50:57], v[146:153], v[34:49], v220, v1 op_sel_hi:[0,0,0]
	s_waitcnt lgkmcnt(0)
	v_mfma_scale_f32_32x32x64_f8f6f4 v[18:33], v[58:65], v[146:153], v[18:33], v220, v1 op_sel_hi:[0,0,0]
	v_add_u32_e32 v50, s3, v69
	v_add_u32_e32 v203, v50, v68
	v_add_u32_e32 v50, s86, v91
	v_add_u32_e32 v227, v50, v90
	s_nop 13
	v_max3_f32 v50, v34, s87, v35
	s_waitcnt vmcnt(0)
	v_max3_f32 v50, v50, v36, v37
	v_max3_f32 v50, v50, v38, v39
	v_max3_f32 v50, v50, v40, v41
	s_waitcnt vmcnt(2)
	ds_write_b128 v224, v[76:79] offset:16384
	s_waitcnt vmcnt(1)
	ds_write_b128 v203, v[80:83]
	s_waitcnt vmcnt(0)
	ds_write_b64 v227, v[88:89]
	s_nop 0
	v_max3_f32 v50, v50, v42, v43
	v_max3_f32 v50, v50, v44, v45
	v_max3_f32 v50, v50, v46, v47
	v_max3_f32 v50, v50, v48, v49
	s_nop 0
	v_max3_f32 v50, v50, v18, v19
	v_max3_f32 v50, v50, v20, v21
	v_max3_f32 v50, v50, v22, v23
	v_max3_f32 v50, v50, v24, v25
	s_nop 0
	v_max3_f32 v50, v50, v26, v27
	v_max3_f32 v50, v50, v28, v29
	v_max3_f32 v50, v50, v30, v31
	v_max3_f32 v50, v50, v32, v33
	s_nop 0
	v_mov_b32_e32 v51, v50
	s_nop 1
	v_permlane32_swap_b32_e32 v50, v51
	v_max_f32_e32 v51, v51, v51
	v_max_f32_e32 v50, v50, v50
	v_max_f32_e32 v50, v50, v51
	v_add_f32_e32 v50, -4.0, v50
	v_sub_f32_e32 v97, v49, v50
	v_sub_f32_e32 v96, v48, v50
	v_sub_f32_e32 v95, v47, v50
	v_sub_f32_e32 v94, v46, v50
	v_sub_f32_e32 v93, v45, v50
	v_sub_f32_e32 v92, v44, v50
	v_sub_f32_e32 v91, v43, v50
	v_sub_f32_e32 v90, v42, v50
	v_sub_f32_e32 v89, v41, v50
	v_sub_f32_e32 v88, v40, v50
	v_sub_f32_e32 v87, v39, v50
	v_sub_f32_e32 v86, v38, v50
	v_sub_f32_e32 v85, v37, v50
	v_sub_f32_e32 v84, v36, v50
	v_sub_f32_e32 v35, v35, v50
	v_sub_f32_e32 v34, v34, v50
	v_sub_f32_e32 v113, v33, v50
	v_sub_f32_e32 v112, v32, v50
	v_sub_f32_e32 v111, v31, v50
	v_sub_f32_e32 v110, v30, v50
	v_sub_f32_e32 v109, v29, v50
	v_sub_f32_e32 v108, v28, v50
	v_sub_f32_e32 v107, v27, v50
	v_sub_f32_e32 v106, v26, v50
	v_sub_f32_e32 v105, v25, v50
	v_sub_f32_e32 v104, v24, v50
	v_sub_f32_e32 v103, v23, v50
	v_sub_f32_e32 v102, v22, v50
	v_sub_f32_e32 v101, v21, v50
	v_sub_f32_e32 v100, v20, v50
	v_sub_f32_e32 v99, v19, v50
	v_sub_f32_e32 v18, v18, v50
	v_sub_f32_e32 v50, 0, v50
	v_mov_b32_e32 v51, v50
	v_mov_b32_e32 v52, v50
	v_mov_b32_e32 v53, v50
	v_mov_b32_e32 v54, v50
	v_mov_b32_e32 v55, v50
	v_mov_b32_e32 v56, v50
	v_mov_b32_e32 v57, v50
	v_mov_b32_e32 v58, v50
	v_mov_b32_e32 v59, v50
	v_mov_b32_e32 v60, v50
	v_mov_b32_e32 v61, v50
	v_mov_b32_e32 v62, v50
	v_mov_b32_e32 v63, v50
	v_mov_b32_e32 v64, v50
	v_mov_b32_e32 v65, v50
	v_mov_b32_e32 v228, 1.0
	v_exp_f32_e32 v82, v34
	v_exp_f32_e32 v83, v35
	s_nop 0
	v_exp_f32_e32 v84, v84
	v_exp_f32_e32 v85, v85
	v_exp_f32_e32 v86, v86
	s_nop 0
	v_exp_f32_e32 v87, v87
	v_exp_f32_e32 v88, v88
	v_exp_f32_e32 v89, v89
	s_nop 0
	v_exp_f32_e32 v90, v90
	v_exp_f32_e32 v91, v91
	v_exp_f32_e32 v92, v92
	s_nop 0
	v_exp_f32_e32 v93, v93
	v_exp_f32_e32 v94, v94
	v_exp_f32_e32 v95, v95
	s_nop 0
	v_exp_f32_e32 v96, v96
	v_exp_f32_e32 v97, v97
	v_exp_f32_e32 v98, v18
	s_nop 0
	v_exp_f32_e32 v99, v99
	v_exp_f32_e32 v100, v100
	v_exp_f32_e32 v101, v101
	s_nop 0
	v_exp_f32_e32 v102, v102
	v_exp_f32_e32 v103, v103
	v_exp_f32_e32 v104, v104
	s_nop 0
	v_exp_f32_e32 v105, v105
	v_exp_f32_e32 v106, v106
	v_exp_f32_e32 v107, v107
	s_nop 0
	v_exp_f32_e32 v108, v108
	v_exp_f32_e32 v109, v109
	v_exp_f32_e32 v110, v110
	s_nop 0
	v_exp_f32_e32 v111, v111
	v_exp_f32_e32 v112, v112
	v_exp_f32_e32 v113, v113
	s_lshl_b32 s4, s4, 9
	s_lshl_b32 s5, s5, 7
	s_or_b32 s4, s4, s5
	v_or_b32_e32 v66, v66, v68
	s_ashr_i32 s5, s4, 31
	v_mov_b32_e32 v166, v188
	v_mov_b32_e32 v167, v189
	v_lshl_add_u64 v[188:189], v[66:67], 0, s[4:5]
	v_mov_b64_e32 v[32:33], v[16:17]
	v_mov_b64_e32 v[48:49], v[16:17]
	v_mov_b64_e32 v[80:81], v[16:17]
	v_mov_b32_e32 v172, v192
	v_mov_b32_e32 v173, v193
	v_lshl_add_u64 v[192:193], s[54:55], 0, v[186:187]
	v_mov_b32_e32 v195, 0
	s_mov_b32 s5, 0x8000
	s_movk_i32 s4, 0x4000
	s_mov_b32 s9, -1
	v_mov_b64_e32 v[30:31], v[14:15]
	v_mov_b64_e32 v[28:29], v[12:13]
	v_mov_b64_e32 v[26:27], v[10:11]
	v_mov_b64_e32 v[24:25], v[8:9]
	v_mov_b64_e32 v[22:23], v[6:7]
	v_mov_b64_e32 v[20:21], v[4:5]
	v_mov_b64_e32 v[18:19], v[2:3]
	v_mov_b64_e32 v[46:47], v[14:15]
	v_mov_b64_e32 v[44:45], v[12:13]
	v_mov_b64_e32 v[42:43], v[10:11]
	v_mov_b64_e32 v[40:41], v[8:9]
	v_mov_b64_e32 v[38:39], v[6:7]
	v_mov_b64_e32 v[36:37], v[4:5]
	v_mov_b64_e32 v[34:35], v[2:3]
	v_mov_b64_e32 v[78:79], v[14:15]
	v_mov_b64_e32 v[76:77], v[12:13]
	v_mov_b64_e32 v[74:75], v[10:11]
	v_mov_b64_e32 v[72:73], v[8:9]
	v_mov_b64_e32 v[70:71], v[6:7]
	v_mov_b64_e32 v[68:69], v[4:5]
	v_mov_b64_e32 v[66:67], v[2:3]
	v_add_u32_e32 v188, 0x1de1d800, v188
	v_add_u32_e32 v192, 0x1cdfd800, v192
	v_add_u32_e32 v189, 0x10000, v188
	s_add_u32 s98, s72, 0x2a302800
	s_addc_u32 s99, s73, 0
	s_waitcnt lgkmcnt(0)
	s_barrier
.LBB0_1733:
	s_mov_b32 s10, s4
	s_mov_b32 s4, s8
	global_load_dwordx4 v[204:207], v192, s[98:99] offset:128
	global_load_dwordx4 v[208:211], v188, s[98:99]
	global_load_dwordx2 v[218:219], v214, s[98:99] offset:-2048
	ds_read_b128 v[118:121], v199 offset:17424
	ds_read_b128 v[114:117], v199 offset:17408
	ds_read_b128 v[130:133], v199 offset:22016
	ds_read_b128 v[134:137], v199 offset:22032
	ds_read_b128 v[156:159], v199 offset:17488
	ds_read_b128 v[238:241], v199 offset:17472
	s_waitcnt lgkmcnt(4)
	v_add_f32_e32 v160, v86, v82
	v_mfma_scale_f32_32x32x64_f8f6f4 v[114:129], v[114:119], v[168:173], v[50:65], v120, v194 op_sel_hi:[0,0,0] cbsz:2 blgp:2
	v_cvt_pk_fp8_f32 v154, v82, v83
	v_cvt_pk_fp8_f32 v155, v98, v99
	v_cvt_pk_fp8_f32 v154, v84, v85 op_sel:[0,0,1]
	v_cvt_pk_fp8_f32 v155, v100, v101 op_sel:[0,0,1]
	v_add_f32_e32 v82, v87, v83
	v_add_f32_e32 v83, v88, v84
	v_permlane32_swap_b32_e32 v154, v155
	ds_read_b128 v[244:247], v199 offset:22080
	ds_read_b128 v[248:251], v199 offset:22096
	s_waitcnt lgkmcnt(3)
	v_mfma_scale_f32_32x32x64_f8f6f4 v[130:145], v[130:135], v[168:173], v[50:65], v136, v194 op_sel_hi:[0,0,0] cbsz:2 blgp:2
	v_add_f32_e32 v84, v89, v85
	v_add_f32_e32 v85, v90, v160
	v_add_f32_e32 v82, v91, v82
	v_mov_b32_e32 v242, v156
	v_mov_b32_e32 v243, v157
	v_add_f32_e32 v83, v92, v83
	v_add_f32_e32 v84, v93, v84
	v_add_f32_e32 v159, v94, v85
	v_add_f32_e32 v160, v95, v82
	v_add_f32_e32 v161, v96, v83
	v_add_f32_e32 v186, v97, v84
	ds_read_b128 v[230:233], v222 offset:5120
	ds_read_b128 v[234:237], v222 offset:5136
	s_waitcnt lgkmcnt(4)
	v_mfma_scale_f32_32x32x64_f8f6f4 v[114:129], v[238:243], v[162:167], v[114:129], v158, v190 op_sel_hi:[0,0,0] cbsz:2 blgp:2
	v_cvt_pk_fp8_f32 v156, v86, v87
	v_cvt_pk_fp8_f32 v157, v102, v103
	v_cvt_pk_fp8_f32 v156, v88, v89 op_sel:[0,0,1]
	v_cvt_pk_fp8_f32 v157, v104, v105 op_sel:[0,0,1]
	v_add_f32_e32 v98, v98, v159
	v_add_f32_e32 v99, v99, v160
	v_permlane32_swap_b32_e32 v156, v157
	v_add_f32_e32 v100, v100, v161
	v_add_f32_e32 v101, v101, v186
	v_add_f32_e32 v98, v102, v98
	ds_read_b128 v[82:85], v222 offset:7680
	ds_read_b128 v[86:89], v222 offset:7696
	s_waitcnt lgkmcnt(4)
	v_mfma_scale_f32_32x32x64_f8f6f4 v[130:145], v[244:249], v[162:167], v[130:145], v250, v190 op_sel_hi:[0,0,0] cbsz:2 blgp:2
	v_cvt_pk_fp8_f32 v158, v90, v91
	v_cvt_pk_fp8_f32 v159, v106, v107
	v_cvt_pk_fp8_f32 v158, v92, v93 op_sel:[0,0,1]
	v_cvt_pk_fp8_f32 v159, v108, v109 op_sel:[0,0,1]
	v_add_f32_e32 v90, v103, v99
	v_add_f32_e32 v91, v104, v100
	v_permlane32_swap_b32_e32 v158, v159
	s_waitcnt lgkmcnt(2)
	v_mfma_scale_f32_32x32x64_f8f6f4 v[114:129], v[230:237], v[146:153], v[114:129], v220, v1 op_sel_hi:[0,0,0]
	v_add_f32_e32 v92, v105, v101
	v_add_f32_e32 v93, v106, v98
	v_add_f32_e32 v90, v107, v90
	s_waitcnt lgkmcnt(0)
	v_mfma_scale_f32_32x32x64_f8f6f4 v[130:145], v[82:89], v[146:153], v[130:145], v220, v1 op_sel_hi:[0,0,0]
	v_add_f32_e32 v91, v108, v91
	v_add_f32_e32 v92, v109, v92
	v_add_f32_e32 v93, v110, v93
	v_add_f32_e32 v90, v111, v90
	v_add_f32_e32 v91, v112, v91
	v_add_f32_e32 v92, v113, v92
	v_cvt_pk_fp8_f32 v160, v94, v95
	v_cvt_pk_fp8_f32 v161, v110, v111
	v_cvt_pk_fp8_f32 v160, v96, v97 op_sel:[0,0,1]
	v_cvt_pk_fp8_f32 v161, v112, v113 op_sel:[0,0,1]
	v_add_f32_e32 v82, v93, v90
	v_add_f32_e32 v83, v91, v92
	v_permlane32_swap_b32_e32 v160, v161
	v_add_f32_e32 v229, v82, v83
	v_mov_b32_e32 v230, v229
	v_add_u32_e32 v82, s5, v224
	s_waitcnt vmcnt(0)
	ds_write_b128 v82, v[204:207]
	ds_write_b128 v225, v[208:211] offset:49152
	ds_write_b64 v226, v[218:219]
	v_add_u32_e32 v98, s4, v191
	ds_read_b128 v[90:93], v98
	ds_read_b128 v[94:97], v98 offset:16
	v_max3_f32 v82, v114, s87, v115
	v_max3_f32 v82, v82, v116, v117
	v_max3_f32 v82, v82, v118, v119
	v_permlane32_swap_b32_e32 v229, v230
	v_max3_f32 v99, v82, v120, v121
	ds_read_b128 v[82:85], v98 offset:2560
	ds_read_b128 v[86:89], v98 offset:2576
	v_max3_f32 v99, v99, v122, v123
	v_max3_f32 v99, v99, v124, v125
	v_max3_f32 v99, v99, v126, v127
	v_max3_f32 v99, v99, v128, v129
	v_max3_f32 v99, v99, v130, v131
	v_max3_f32 v99, v99, v132, v133
	v_max3_f32 v99, v99, v134, v135
	v_max3_f32 v99, v99, v136, v137
	v_max3_f32 v99, v99, v138, v139
	v_max3_f32 v99, v99, v140, v141
	v_max3_f32 v99, v99, v142, v143
	v_max3_f32 v99, v99, v144, v145
	v_mov_b32_e32 v100, v99
	v_mov_b32_e32 v186, 1.0
	s_nop 0
	v_permlane32_swap_b32_e32 v99, v100
	v_max_f32_e32 v99, v99, v100
	v_cmp_ge_f32_e32 vcc, s88, v99
	s_cmp_eq_u64 vcc, exec
	s_cbranch_scc1 .LBB0_1735
	v_add_f32_e32 v99, -4.0, v99
	v_max_f32_e32 v99, 0, v99
	v_exp_f32_e64 v186, -v99
	v_sub_f32_e32 v129, v129, v99
	v_sub_f32_e32 v128, v128, v99
	v_sub_f32_e32 v127, v127, v99
	v_sub_f32_e32 v126, v126, v99
	v_sub_f32_e32 v125, v125, v99
	v_sub_f32_e32 v124, v124, v99
	v_sub_f32_e32 v123, v123, v99
	v_sub_f32_e32 v122, v122, v99
	v_sub_f32_e32 v121, v121, v99
	v_sub_f32_e32 v120, v120, v99
	v_sub_f32_e32 v119, v119, v99
	v_sub_f32_e32 v118, v118, v99
	v_sub_f32_e32 v117, v117, v99
	v_sub_f32_e32 v116, v116, v99
	v_sub_f32_e32 v115, v115, v99
	v_sub_f32_e32 v114, v114, v99
	v_sub_f32_e32 v145, v145, v99
	v_sub_f32_e32 v144, v144, v99
	v_sub_f32_e32 v143, v143, v99
	v_sub_f32_e32 v142, v142, v99
	v_sub_f32_e32 v141, v141, v99
	v_sub_f32_e32 v140, v140, v99
	v_sub_f32_e32 v139, v139, v99
	v_sub_f32_e32 v138, v138, v99
	v_sub_f32_e32 v137, v137, v99
	v_sub_f32_e32 v136, v136, v99
	v_sub_f32_e32 v135, v135, v99
	v_sub_f32_e32 v134, v134, v99
	v_sub_f32_e32 v133, v133, v99
	v_sub_f32_e32 v132, v132, v99
	v_sub_f32_e32 v131, v131, v99
	v_sub_f32_e32 v130, v130, v99
	v_sub_f32_e32 v65, v65, v99
	v_sub_f32_e32 v64, v64, v99
	v_sub_f32_e32 v63, v63, v99
	v_sub_f32_e32 v62, v62, v99
	v_sub_f32_e32 v61, v61, v99
	v_sub_f32_e32 v60, v60, v99
	v_sub_f32_e32 v59, v59, v99
	v_sub_f32_e32 v58, v58, v99
	v_sub_f32_e32 v57, v57, v99
	v_sub_f32_e32 v56, v56, v99
	v_sub_f32_e32 v55, v55, v99
	v_sub_f32_e32 v54, v54, v99
	v_sub_f32_e32 v53, v53, v99
	v_sub_f32_e32 v52, v52, v99
	v_sub_f32_e32 v51, v51, v99
	v_sub_f32_e32 v50, v50, v99

.LBB0_1737:
	s_barrier
	global_load_dwordx4 v[204:207], v192, s[98:99] offset:192
	global_load_dwordx4 v[208:211], v189, s[98:99]
	global_load_dwordx2 v[196:197], v214, s[98:99] offset:2048
	ds_read_b128 v[86:89], v223 offset:49168
	ds_read_b128 v[82:85], v223 offset:49152
	ds_read_b128 v[98:101], v223 offset:53760
	ds_read_b128 v[102:105], v223 offset:53776
	ds_read_b128 v[156:159], v223 offset:49232
	ds_read_b128 v[240:243], v223 offset:49216
	s_waitcnt lgkmcnt(4)
	v_add_f32_e32 v160, v118, v114
	v_mfma_scale_f32_32x32x64_f8f6f4 v[82:97], v[82:87], v[174:179], v[50:65], v88, v198 op_sel_hi:[0,0,0] cbsz:2 blgp:2
	v_cvt_pk_fp8_f32 v154, v114, v115
	v_cvt_pk_fp8_f32 v155, v130, v131
	v_cvt_pk_fp8_f32 v154, v116, v117 op_sel:[0,0,1]
	v_cvt_pk_fp8_f32 v155, v132, v133 op_sel:[0,0,1]
	v_add_f32_e32 v114, v119, v115
	v_add_f32_e32 v115, v120, v116
	v_permlane32_swap_b32_e32 v154, v155
	ds_read_b128 v[246:249], v223 offset:53824
	ds_read_b128 v[216:219], v223 offset:53840
	s_waitcnt lgkmcnt(3)
	v_mfma_scale_f32_32x32x64_f8f6f4 v[98:113], v[98:103], v[174:179], v[50:65], v104, v198 op_sel_hi:[0,0,0] cbsz:2 blgp:2
	v_add_f32_e32 v116, v121, v117
	v_add_f32_e32 v117, v122, v160
	v_add_f32_e32 v114, v123, v114
	v_mov_b32_e32 v244, v156
	v_mov_b32_e32 v245, v157
	v_add_f32_e32 v115, v124, v115
	v_add_f32_e32 v116, v125, v116
	v_add_f32_e32 v159, v126, v117
	v_add_f32_e32 v160, v127, v114
	v_add_f32_e32 v161, v128, v115
	v_add_f32_e32 v200, v129, v116
	ds_read_b128 v[232:235], v222
	ds_read_b128 v[236:239], v222 offset:16
	s_waitcnt lgkmcnt(4)
	v_mfma_scale_f32_32x32x64_f8f6f4 v[82:97], v[240:245], v[180:185], v[82:97], v158, v202 op_sel_hi:[0,0,0] cbsz:2 blgp:2
	v_cvt_pk_fp8_f32 v156, v118, v119
	v_cvt_pk_fp8_f32 v157, v134, v135
	v_cvt_pk_fp8_f32 v156, v120, v121 op_sel:[0,0,1]
	v_cvt_pk_fp8_f32 v157, v136, v137 op_sel:[0,0,1]
	v_add_f32_e32 v130, v130, v159
	v_add_f32_e32 v131, v131, v160
	v_permlane32_swap_b32_e32 v156, v157
	s_waitcnt lgkmcnt(2)
	v_mov_b32_e32 v250, v216
	v_mov_b32_e32 v251, v217
	v_add_f32_e32 v132, v132, v161
	v_add_f32_e32 v133, v133, v200
	v_add_f32_e32 v130, v134, v130
	ds_read_b128 v[114:117], v222 offset:2560
	ds_read_b128 v[118:121], v222 offset:2576
	v_mfma_scale_f32_32x32x64_f8f6f4 v[98:113], v[246:251], v[180:185], v[98:113], v218, v202 op_sel_hi:[0,0,0] cbsz:2 blgp:2
	v_cvt_pk_fp8_f32 v158, v122, v123
	v_cvt_pk_fp8_f32 v159, v138, v139
	v_cvt_pk_fp8_f32 v158, v124, v125 op_sel:[0,0,1]
	v_cvt_pk_fp8_f32 v159, v140, v141 op_sel:[0,0,1]
	v_add_f32_e32 v122, v135, v131
	v_add_f32_e32 v123, v136, v132
	v_permlane32_swap_b32_e32 v158, v159
	s_waitcnt lgkmcnt(2)
	v_mfma_scale_f32_32x32x64_f8f6f4 v[82:97], v[232:239], v[146:153], v[82:97], v220, v1 op_sel_hi:[0,0,0]
	v_add_f32_e32 v124, v137, v133
	v_add_f32_e32 v125, v138, v130
	v_add_f32_e32 v122, v139, v122
	s_waitcnt lgkmcnt(0)
	v_mfma_scale_f32_32x32x64_f8f6f4 v[98:113], v[114:121], v[146:153], v[98:113], v220, v1 op_sel_hi:[0,0,0]
	v_add_f32_e32 v123, v140, v123
	v_add_f32_e32 v124, v141, v124
	v_add_f32_e32 v125, v142, v125
	v_add_f32_e32 v122, v143, v122
	v_add_f32_e32 v123, v144, v123
	v_add_f32_e32 v124, v145, v124
	v_cvt_pk_fp8_f32 v160, v126, v127
	v_cvt_pk_fp8_f32 v161, v142, v143
	v_cvt_pk_fp8_f32 v160, v128, v129 op_sel:[0,0,1]
	v_cvt_pk_fp8_f32 v161, v144, v145 op_sel:[0,0,1]
	v_add_f32_e32 v114, v125, v122
	v_add_f32_e32 v115, v123, v124
	v_permlane32_swap_b32_e32 v160, v161
	v_add_f32_e32 v130, v114, v115
	v_mov_b32_e32 v131, v130
	v_add_u32_e32 v114, s4, v224
	s_waitcnt vmcnt(0)
	ds_write_b128 v114, v[204:207]
	ds_write_b128 v203, v[208:211]
	ds_write_b64 v227, v[196:197]
	v_add_u32_e32 v132, s10, v191
	ds_read_b128 v[122:125], v132
	ds_read_b128 v[126:129], v132 offset:16
	v_max3_f32 v114, v82, s87, v83
	v_max3_f32 v114, v114, v84, v85
	v_max3_f32 v114, v114, v86, v87
	v_permlane32_swap_b32_e32 v130, v131
	v_max3_f32 v133, v114, v88, v89
	ds_read_b128 v[114:117], v132 offset:2560
	ds_read_b128 v[118:121], v132 offset:2576
	v_max3_f32 v133, v133, v90, v91
	v_max3_f32 v133, v133, v92, v93
	v_max3_f32 v133, v133, v94, v95
	v_max3_f32 v133, v133, v96, v97
	v_max3_f32 v133, v133, v98, v99
	v_max3_f32 v133, v133, v100, v101
	v_max3_f32 v133, v133, v102, v103
	v_max3_f32 v133, v133, v104, v105
	v_max3_f32 v133, v133, v106, v107
	v_max3_f32 v133, v133, v108, v109
	v_max3_f32 v133, v133, v110, v111
	v_max3_f32 v133, v133, v112, v113
	v_mov_b32_e32 v134, v133
	v_mov_b32_e32 v138, 1.0
	s_nop 0
	v_permlane32_swap_b32_e32 v133, v134
	v_max_f32_e32 v133, v133, v134
	v_cmp_ge_f32_e32 vcc, s88, v133
	s_cmp_eq_u64 vcc, exec
	s_cbranch_scc1 .LBB0_1739
	v_add_f32_e32 v133, -4.0, v133
	v_max_f32_e32 v133, 0, v133
	v_exp_f32_e64 v138, -v133
	v_sub_f32_e32 v97, v97, v133
	v_sub_f32_e32 v96, v96, v133
	v_sub_f32_e32 v95, v95, v133
	v_sub_f32_e32 v94, v94, v133
	v_sub_f32_e32 v93, v93, v133
	v_sub_f32_e32 v92, v92, v133
	v_sub_f32_e32 v91, v91, v133
	v_sub_f32_e32 v90, v90, v133
	v_sub_f32_e32 v89, v89, v133
	v_sub_f32_e32 v88, v88, v133
	v_sub_f32_e32 v87, v87, v133
	v_sub_f32_e32 v86, v86, v133
	v_sub_f32_e32 v85, v85, v133
	v_sub_f32_e32 v84, v84, v133
	v_sub_f32_e32 v83, v83, v133
	v_sub_f32_e32 v82, v82, v133
	v_sub_f32_e32 v113, v113, v133
	v_sub_f32_e32 v112, v112, v133
	v_sub_f32_e32 v111, v111, v133
	v_sub_f32_e32 v110, v110, v133
	v_sub_f32_e32 v109, v109, v133
	v_sub_f32_e32 v108, v108, v133
	v_sub_f32_e32 v107, v107, v133
	v_sub_f32_e32 v106, v106, v133
	v_sub_f32_e32 v105, v105, v133
	v_sub_f32_e32 v104, v104, v133
	v_sub_f32_e32 v103, v103, v133
	v_sub_f32_e32 v102, v102, v133
	v_sub_f32_e32 v101, v101, v133
	v_sub_f32_e32 v100, v100, v133
	v_sub_f32_e32 v99, v99, v133
	v_sub_f32_e32 v98, v98, v133
	v_sub_f32_e32 v65, v65, v133
	v_sub_f32_e32 v64, v64, v133
	v_sub_f32_e32 v63, v63, v133
	v_sub_f32_e32 v62, v62, v133
	v_sub_f32_e32 v61, v61, v133
	v_sub_f32_e32 v60, v60, v133
	v_sub_f32_e32 v59, v59, v133
	v_sub_f32_e32 v58, v58, v133
	v_sub_f32_e32 v57, v57, v133
	v_sub_f32_e32 v56, v56, v133
	v_sub_f32_e32 v55, v55, v133
	v_sub_f32_e32 v54, v54, v133
	v_sub_f32_e32 v53, v53, v133
	v_sub_f32_e32 v52, v52, v133
	v_sub_f32_e32 v51, v51, v133
	v_sub_f32_e32 v50, v50, v133

.LBB0_1741:
	v_add_f32_e32 v114, v229, v230
	v_add_u32_e32 v188, 0x20000, v188
	v_add_u32_e32 v189, 0x20000, v189
	v_fmac_f32_e32 v114, v195, v228
	v_add_f32_e32 v195, v130, v131
	s_add_i32 s9, s9, 2
	v_add_u32_e32 v192, 0x80, v192
	v_fmac_f32_e32 v195, v114, v186
	s_cmpk_gt_u32 s9, 0xfc
	v_add_u32_e32 v214, 0x2000, v214
	s_barrier
	s_cbranch_scc1 .LBB0_1743
	s_mov_b32 s8, s5
	s_mov_b32 s5, s10
	v_mov_b32_e32 v228, v138
	s_branch .LBB0_1733

	.amdhsa_kernel _Z3fwd4Args
		.amdhsa_group_segment_fixed_size 0
		.amdhsa_private_segment_fixed_size 0
		.amdhsa_kernarg_size 448
		.amdhsa_user_sgpr_count 2
		.amdhsa_user_sgpr_dispatch_ptr 0
		.amdhsa_user_sgpr_queue_ptr 0
		.amdhsa_user_sgpr_kernarg_segment_ptr 1
		.amdhsa_user_sgpr_dispatch_id 0
		.amdhsa_user_sgpr_kernarg_preload_length 0
		.amdhsa_user_sgpr_kernarg_preload_offset 0
		.amdhsa_user_sgpr_private_segment_size 0
		.amdhsa_uses_dynamic_stack 0
		.amdhsa_enable_private_segment 0
		.amdhsa_system_sgpr_workgroup_id_x 1
		.amdhsa_system_sgpr_workgroup_id_y 0
		.amdhsa_system_sgpr_workgroup_id_z 0
		.amdhsa_system_sgpr_workgroup_info 0
		.amdhsa_system_vgpr_workitem_id 0
		.amdhsa_next_free_vgpr 255
		.amdhsa_next_free_sgpr 100
		.amdhsa_accum_offset 256
		.amdhsa_reserve_vcc 1
		.amdhsa_float_round_mode_32 0
		.amdhsa_float_round_mode_16_64 0
		.amdhsa_float_denorm_mode_32 3
		.amdhsa_float_denorm_mode_16_64 3
		.amdhsa_dx10_clamp 1
		.amdhsa_ieee_mode 1
		.amdhsa_fp16_overflow 0
		.amdhsa_tg_split 0
		.amdhsa_exception_fp_ieee_invalid_op 0
		.amdhsa_exception_fp_denorm_src 0
		.amdhsa_exception_fp_ieee_div_zero 0
		.amdhsa_exception_fp_ieee_overflow 0
		.amdhsa_exception_fp_ieee_underflow 0
		.amdhsa_exception_fp_ieee_inexact 0
		.amdhsa_exception_int_div_zero 0
	.end_amdhsa_kernel

.Lfunc_end0:
	.size	_Z3fwd4Args, .Lfunc_end0-_Z3fwd4Args
	.set _Z3fwd4Args.num_vgpr, 255
	.set _Z3fwd4Args.num_agpr, 0
	.set _Z3fwd4Args.numbered_sgpr, 100
	.set _Z3fwd4Args.num_named_barrier, 0
	.set _Z3fwd4Args.private_seg_size, 0
	.set _Z3fwd4Args.uses_vcc, 1
	.set _Z3fwd4Args.uses_flat_scratch, 0
	.set _Z3fwd4Args.has_dyn_sized_stack, 0
	.set _Z3fwd4Args.has_recursion, 0
	.set _Z3fwd4Args.has_indirect_call, 0

amdhsa.kernels:
  - .agpr_count:     0
    .args:
      - .offset:         0
        .size:           192
        .value_kind:     by_value
      - .offset:         192
        .size:           4
        .value_kind:     hidden_block_count_x
      - .offset:         196
        .size:           4
        .value_kind:     hidden_block_count_y
      - .offset:         200
        .size:           4
        .value_kind:     hidden_block_count_z
      - .offset:         204
        .size:           2
        .value_kind:     hidden_group_size_x
      - .offset:         206
        .size:           2
        .value_kind:     hidden_group_size_y
      - .offset:         208
        .size:           2
        .value_kind:     hidden_group_size_z
      - .offset:         210
        .size:           2
        .value_kind:     hidden_remainder_x
      - .offset:         212
        .size:           2
        .value_kind:     hidden_remainder_y
      - .offset:         214
        .size:           2
        .value_kind:     hidden_remainder_z
      - .offset:         232
        .size:           8
        .value_kind:     hidden_global_offset_x
      - .offset:         240
        .size:           8
        .value_kind:     hidden_global_offset_y
      - .offset:         248
        .size:           8
        .value_kind:     hidden_global_offset_z
      - .offset:         256
        .size:           2
        .value_kind:     hidden_grid_dims
      - .offset:         312
        .size:           4
        .value_kind:     hidden_dynamic_lds_size
    .group_segment_fixed_size: 0
    .kernarg_segment_align: 8
    .kernarg_segment_size: 448
    .language:       OpenCL C
    .language_version:
      - 2
      - 0
    .max_flat_workgroup_size: 512
    .name:           _Z3fwd4Args
    .private_segment_fixed_size: 0
    .sgpr_count:     106
    .sgpr_spill_count: 77
    .symbol:         _Z3fwd4Args.kd
    .uniform_work_group_size: 1
    .uses_dynamic_stack: false
    .vgpr_count:     255
    .vgpr_spill_count: 0
    .wavefront_size: 64
